# grid barrier: acquire-side buffer_inv sc1 issued before spinning on the release word (workgroup is parked, only sc1 polls in flight) instead of after; stacked on the GEMM loop edits
# speedup vs baseline: 1.0170x; 1.0170x over previous
.LBB0_60:
	s_or_b64 exec, exec, s[6:7]
	v_cvt_f32_u32_e32 v4, v2
	s_waitcnt vmcnt(0)
	v_readfirstlane_b32 s4, v3
	v_sub_u32_e32 v3, 0, v2
	v_rcp_iflag_f32_e32 v4, v4
	v_add_u32_e32 v5, s4, v1
	v_mul_f32_e32 v4, 0x4f7ffffe, v4
	v_cvt_u32_f32_e32 v4, v4
	v_mul_lo_u32 v1, v3, v4
	v_mul_hi_u32 v1, v4, v1
	v_add_u32_e32 v1, v4, v1
	v_mul_hi_u32 v1, v5, v1
	v_mul_lo_u32 v3, v1, v2
	v_sub_u32_e32 v3, v5, v3
	v_add_u32_e32 v4, 1, v1
	v_cmp_ge_u32_e32 vcc, v3, v2
	s_nop 1
	v_cndmask_b32_e32 v1, v1, v4, vcc
	v_sub_u32_e32 v4, v3, v2
	v_cndmask_b32_e32 v3, v3, v4, vcc
	v_add_u32_e32 v4, 1, v1
	v_cmp_ge_u32_e32 vcc, v3, v2
	v_add_u32_e32 v3, 1, v5
	s_nop 0
	v_cndmask_b32_e32 v1, v1, v4, vcc
	v_mul_lo_u32 v4, v2, v1
	v_add_u32_e32 v2, v4, v2
	v_cmp_ne_u32_e32 vcc, v3, v2
	s_and_saveexec_b64 s[4:5], vcc
	s_xor_b64 s[4:5], exec, s[4:5]
	s_cbranch_execz .LBB0_74
	s_waitcnt lgkmcnt(0)
	v_mov_b32_e32 v0, 0x2000
	buffer_inv sc1
	global_load_dword v0, v0, s[2:3] offset:1024 sc1
	s_add_u32 s10, s2, 0x2400
	s_addc_u32 s11, s3, 0
	s_waitcnt vmcnt(0)
	v_cmp_eq_u32_e32 vcc, v0, v1
	s_and_saveexec_b64 s[6:7], vcc
	s_cbranch_execz .LBB0_73
	s_add_u32 s8, s90, 0x4200
	s_addc_u32 s9, s91, 0
	s_mov_b32 s19, 1
	s_mov_b64 s[12:13], 0
	v_mov_b32_e32 v0, 0
	s_branch .LBB0_64

.LBB0_73:
	s_or_b64 exec, exec, s[6:7]
	s_waitcnt vmcnt(0)
	s_waitcnt vmcnt(0)
.LBB0_74:
	s_andn2_saveexec_b64 s[4:5], s[4:5]
	s_cbranch_execz .LBB0_94
	s_mov_b64 s[4:5], exec
	s_mov_b32 s99, 0
	buffer_wbl2 sc1
	s_waitcnt lgkmcnt(0)
	s_waitcnt vmcnt(0)
	v_mbcnt_lo_u32_b32 v1, s4, 0
	v_mbcnt_hi_u32_b32 v1, s5, v1
	v_cmp_eq_u32_e32 vcc, 0, v1
	s_and_saveexec_b64 s[6:7], vcc
	s_cbranch_execz .LBB0_77
	s_bcnt1_i32_b64 s4, s[4:5]
	v_mov_b32_e32 v2, 0x7000
	v_mov_b32_e32 v3, s4
	global_atomic_add v2, v2, v3, s[90:91] offset:1024 sc0
.LBB0_77:
	s_or_b64 exec, exec, s[6:7]
	v_cvt_f32_u32_e32 v3, v0
	s_waitcnt vmcnt(0)
	v_readfirstlane_b32 s4, v2
	s_add_u32 s6, s90, 0x7500
	s_addc_u32 s7, s91, 0
	v_rcp_iflag_f32_e32 v3, v3
	v_add_u32_e32 v1, s4, v1
	v_add_u32_e32 v4, 1, v1
	s_mov_b64 s[8:9], -1
	v_mul_f32_e32 v2, 0x4f7ffffe, v3
	v_cvt_u32_f32_e32 v2, v2
	v_sub_u32_e32 v3, 0, v0
	v_mul_lo_u32 v3, v3, v2
	v_mul_hi_u32 v3, v2, v3
	v_add_u32_e32 v2, v2, v3
	v_mul_hi_u32 v2, v1, v2
	v_mul_lo_u32 v3, v2, v0
	v_sub_u32_e32 v1, v1, v3
	v_add_u32_e32 v5, 1, v2
	v_cmp_ge_u32_e32 vcc, v1, v0
	v_sub_u32_e32 v3, v1, v0
	s_nop 0
	v_cndmask_b32_e32 v2, v2, v5, vcc
	v_cndmask_b32_e32 v1, v1, v3, vcc
	v_add_u32_e32 v3, 1, v2
	v_cmp_ge_u32_e32 vcc, v1, v0
	s_nop 1
	v_cndmask_b32_e32 v2, v2, v3, vcc
	v_mul_lo_u32 v1, v0, v2
	v_add_u32_e32 v0, v1, v0
	v_cmp_ne_u32_e32 vcc, v4, v0
	v_mov_b64_e32 v[0:1], s[6:7]
	s_and_saveexec_b64 s[4:5], vcc
	s_cbranch_execz .LBB0_89
	v_mov_b32_e32 v0, 0
	buffer_inv sc1
	s_mov_b32 s99, 1
	global_load_dword v1, v0, s[6:7] sc1
	s_mov_b64 s[12:13], 0
	s_waitcnt vmcnt(0)
	v_cmp_eq_u32_e32 vcc, v1, v2
	s_and_saveexec_b64 s[10:11], vcc
	s_cbranch_execz .LBB0_88
	s_add_u32 s8, s90, 0x4200
	s_addc_u32 s9, s91, 0
	s_mov_b32 s19, 1
	s_branch .LBB0_81

.LBB0_91:
	s_or_b64 exec, exec, s[4:5]
	s_mov_b64 s[4:5], exec
	v_mbcnt_lo_u32_b32 v0, s4, 0
	v_mbcnt_hi_u32_b32 v0, s5, v0
	v_cmp_eq_u32_e32 vcc, 0, v0
	s_waitcnt vmcnt(0)
	s_cmp_lg_u32 s99, 0
	s_cbranch_scc1 .Lbi_skip_0
	buffer_inv sc1
.Lbi_skip_0:
	s_and_saveexec_b64 s[6:7], vcc
	s_cbranch_execz .LBB0_93
	s_bcnt1_i32_b64 s4, s[4:5]
	v_mov_b32_e32 v0, 0x2000
	v_mov_b32_e32 v1, s4
	global_atomic_add v0, v1, s[2:3] offset:1024

.LBB0_898:
	s_or_b64 exec, exec, s[6:7]
	v_cvt_f32_u32_e32 v4, v2
	s_waitcnt vmcnt(0)
	v_readfirstlane_b32 s4, v3
	v_sub_u32_e32 v3, 0, v2
	v_rcp_iflag_f32_e32 v4, v4
	v_add_u32_e32 v5, s4, v1
	v_mul_f32_e32 v4, 0x4f7ffffe, v4
	v_cvt_u32_f32_e32 v4, v4
	v_mul_lo_u32 v1, v3, v4
	v_mul_hi_u32 v1, v4, v1
	v_add_u32_e32 v1, v4, v1
	v_mul_hi_u32 v1, v5, v1
	v_mul_lo_u32 v3, v1, v2
	v_sub_u32_e32 v3, v5, v3
	v_add_u32_e32 v4, 1, v1
	v_cmp_ge_u32_e32 vcc, v3, v2
	s_nop 1
	v_cndmask_b32_e32 v1, v1, v4, vcc
	v_sub_u32_e32 v4, v3, v2
	v_cndmask_b32_e32 v3, v3, v4, vcc
	v_add_u32_e32 v4, 1, v1
	v_cmp_ge_u32_e32 vcc, v3, v2
	v_add_u32_e32 v3, 1, v5
	s_nop 0
	v_cndmask_b32_e32 v1, v1, v4, vcc
	v_mul_lo_u32 v4, v2, v1
	v_add_u32_e32 v2, v4, v2
	v_cmp_ne_u32_e32 vcc, v3, v2
	s_and_saveexec_b64 s[4:5], vcc
	s_xor_b64 s[4:5], exec, s[4:5]
	s_cbranch_execz .LBB0_912
	s_waitcnt lgkmcnt(0)
	v_mov_b32_e32 v0, 0x2000
	buffer_inv sc1
	global_load_dword v0, v0, s[2:3] offset:1024 sc1
	s_add_u32 s14, s2, 0x2400
	s_addc_u32 s15, s3, 0
	s_waitcnt vmcnt(0)
	v_cmp_eq_u32_e32 vcc, v0, v1
	s_and_saveexec_b64 s[6:7], vcc
	s_cbranch_execz .LBB0_911
	s_add_u32 s8, s90, 0x4200
	s_addc_u32 s9, s91, 0
	s_mov_b32 s33, 1
	s_mov_b64 s[28:29], 0
	v_mov_b32_e32 v0, 0
	s_branch .LBB0_902

.LBB0_915:
	s_or_b64 exec, exec, s[6:7]
	v_cvt_f32_u32_e32 v3, v0
	s_waitcnt vmcnt(0)
	v_readfirstlane_b32 s4, v2
	s_add_u32 s6, s90, 0x7500
	s_addc_u32 s7, s91, 0
	v_rcp_iflag_f32_e32 v3, v3
	v_add_u32_e32 v1, s4, v1
	v_add_u32_e32 v4, 1, v1
	s_mov_b64 s[8:9], -1
	v_mul_f32_e32 v2, 0x4f7ffffe, v3
	v_cvt_u32_f32_e32 v2, v2
	v_sub_u32_e32 v3, 0, v0
	v_mul_lo_u32 v3, v3, v2
	v_mul_hi_u32 v3, v2, v3
	v_add_u32_e32 v2, v2, v3
	v_mul_hi_u32 v2, v1, v2
	v_mul_lo_u32 v3, v2, v0
	v_sub_u32_e32 v1, v1, v3
	v_add_u32_e32 v5, 1, v2
	v_cmp_ge_u32_e32 vcc, v1, v0
	v_sub_u32_e32 v3, v1, v0
	s_nop 0
	v_cndmask_b32_e32 v2, v2, v5, vcc
	v_cndmask_b32_e32 v1, v1, v3, vcc
	v_add_u32_e32 v3, 1, v2
	v_cmp_ge_u32_e32 vcc, v1, v0
	s_nop 1
	v_cndmask_b32_e32 v2, v2, v3, vcc
	v_mul_lo_u32 v1, v0, v2
	v_add_u32_e32 v0, v1, v0
	v_cmp_ne_u32_e32 vcc, v4, v0
	v_mov_b64_e32 v[0:1], s[6:7]
	s_and_saveexec_b64 s[4:5], vcc
	s_cbranch_execz .LBB0_927
	v_mov_b32_e32 v0, 0
	buffer_inv sc1
	s_mov_b32 s99, 1
	global_load_dword v1, v0, s[6:7] sc1
	s_mov_b64 s[28:29], 0
	s_waitcnt vmcnt(0)
	v_cmp_eq_u32_e32 vcc, v1, v2
	s_and_saveexec_b64 s[14:15], vcc
	s_cbranch_execz .LBB0_926
	s_add_u32 s8, s90, 0x4200
	s_addc_u32 s9, s91, 0
	s_mov_b32 s33, 1
	s_branch .LBB0_919

.LBB0_1070:
	s_or_b64 exec, exec, s[6:7]
	v_cvt_f32_u32_e32 v4, v2
	s_waitcnt vmcnt(0)
	v_readfirstlane_b32 s4, v3
	v_sub_u32_e32 v3, 0, v2
	v_rcp_iflag_f32_e32 v4, v4
	v_add_u32_e32 v5, s4, v1
	v_mul_f32_e32 v4, 0x4f7ffffe, v4
	v_cvt_u32_f32_e32 v4, v4
	v_mul_lo_u32 v1, v3, v4
	v_mul_hi_u32 v1, v4, v1
	v_add_u32_e32 v1, v4, v1
	v_mul_hi_u32 v1, v5, v1
	v_mul_lo_u32 v3, v1, v2
	v_sub_u32_e32 v3, v5, v3
	v_add_u32_e32 v4, 1, v1
	v_cmp_ge_u32_e32 vcc, v3, v2
	s_nop 1
	v_cndmask_b32_e32 v1, v1, v4, vcc
	v_sub_u32_e32 v4, v3, v2
	v_cndmask_b32_e32 v3, v3, v4, vcc
	v_add_u32_e32 v4, 1, v1
	v_cmp_ge_u32_e32 vcc, v3, v2
	v_add_u32_e32 v3, 1, v5
	s_nop 0
	v_cndmask_b32_e32 v1, v1, v4, vcc
	v_mul_lo_u32 v4, v2, v1
	v_add_u32_e32 v2, v4, v2
	v_cmp_ne_u32_e32 vcc, v3, v2
	s_and_saveexec_b64 s[4:5], vcc
	s_xor_b64 s[4:5], exec, s[4:5]
	s_cbranch_execz .LBB0_1084
	s_waitcnt lgkmcnt(0)
	v_mov_b32_e32 v0, 0x2000
	buffer_inv sc1
	global_load_dword v0, v0, s[2:3] offset:1024 sc1
	s_add_u32 s10, s2, 0x2400
	s_addc_u32 s11, s3, 0
	s_waitcnt vmcnt(0)
	v_cmp_eq_u32_e32 vcc, v0, v1
	s_and_saveexec_b64 s[6:7], vcc
	s_cbranch_execz .LBB0_1083
	s_add_u32 s8, s90, 0x4200
	s_addc_u32 s9, s91, 0
	s_mov_b32 s19, 1
	s_mov_b64 s[14:15], 0
	v_mov_b32_e32 v0, 0
	s_branch .LBB0_1074

.LBB0_1087:
	s_or_b64 exec, exec, s[6:7]
	v_cvt_f32_u32_e32 v3, v0
	s_waitcnt vmcnt(0)
	v_readfirstlane_b32 s4, v2
	s_add_u32 s6, s90, 0x7500
	s_addc_u32 s7, s91, 0
	v_rcp_iflag_f32_e32 v3, v3
	v_add_u32_e32 v1, s4, v1
	v_add_u32_e32 v4, 1, v1
	s_mov_b64 s[8:9], -1
	v_mul_f32_e32 v2, 0x4f7ffffe, v3
	v_cvt_u32_f32_e32 v2, v2
	v_sub_u32_e32 v3, 0, v0
	v_mul_lo_u32 v3, v3, v2
	v_mul_hi_u32 v3, v2, v3
	v_add_u32_e32 v2, v2, v3
	v_mul_hi_u32 v2, v1, v2
	v_mul_lo_u32 v3, v2, v0
	v_sub_u32_e32 v1, v1, v3
	v_add_u32_e32 v5, 1, v2
	v_cmp_ge_u32_e32 vcc, v1, v0
	v_sub_u32_e32 v3, v1, v0
	s_nop 0
	v_cndmask_b32_e32 v2, v2, v5, vcc
	v_cndmask_b32_e32 v1, v1, v3, vcc
	v_add_u32_e32 v3, 1, v2
	v_cmp_ge_u32_e32 vcc, v1, v0
	s_nop 1
	v_cndmask_b32_e32 v2, v2, v3, vcc
	v_mul_lo_u32 v1, v0, v2
	v_add_u32_e32 v0, v1, v0
	v_cmp_ne_u32_e32 vcc, v4, v0
	v_mov_b64_e32 v[0:1], s[6:7]
	s_and_saveexec_b64 s[4:5], vcc
	s_cbranch_execz .LBB0_1099
	v_mov_b32_e32 v0, 0
	buffer_inv sc1
	s_mov_b32 s99, 1
	global_load_dword v1, v0, s[6:7] sc1
	s_mov_b64 s[14:15], 0
	s_waitcnt vmcnt(0)
	v_cmp_eq_u32_e32 vcc, v1, v2
	s_and_saveexec_b64 s[10:11], vcc
	s_cbranch_execz .LBB0_1098
	s_add_u32 s8, s90, 0x4200
	s_addc_u32 s9, s91, 0
	s_mov_b32 s19, 1
	s_branch .LBB0_1091
